# PEER u sweep: next u slice touched by one wave per workgroup during the LAST item of each phase (late L2 prefetch)
# speedup vs baseline: 1.0118x; 1.0118x over previous
; #define LAS __attribute__((address_space(3)))
; #define PB_RECS(rv, t, q) do { rv = *(const LAS recv_t*)(L + PW_REC + (t) * 512 + (g16 + NPB * (q)) * 4); } while (0)
; #define PB_LOADU(buf, T8, rv, soff) do { _Pragma("unroll") for (int i_ = 0; i_ < 4; ++i_) { \
;       int oa_; asm("v_mad_u32_u16 %0, %1, %2, %3" : "=v"(oa_) : "v"(rv[i_]), "s"(128), "v"(lo16)); \
;       buf[i_] = __builtin_bit_cast(v4u, __builtin_amdgcn_raw_buffer_load_b128(T8, oa_, soff, 0)); } } while (0)
; __device__ __forceinline__ void peer_block(int tok0, float* X1, const unsigned short* X1B, const int* TKI, const float* TKS, __amdgpu_buffer_rsrc_t U8r, __amdgpu_buffer_rsrc_t V6, const float* USC, const float* VSC,
;                                            const float* finw, pw_ptr L, int lane) {
;     ...
;         for (int it = 0; it < NSU * PT; ++it) {
;             const int c = it / PT, t = it - c * PT; const int soff = c * SLU;
;             const int itn = it + 1, cn = itn / PT, tn = itn - cn * PT;
;             int rq[4];
;             xq = *(const LAS v4u*)(L + PW_Y + t * 1024 + 128 * c + 16 * m);
; #pragma unroll
;             for (int q = 0; q < 4; ++q) {
;                 const int qa = q + NBU - 1;
;                 if (qa < 4) { PB_RECS(rv, t, qa); PB_LOADU(bu[qa % NBU], U8r, rv, soff); }
;                 else if (itn < NSU * PT) { PB_RECS(rv, tn, qa - 4); PB_LOADU(bu[qa % NBU], U8r, rv, cn * SLU); }
;                 rq[q] = pb_u_part(bu[q % NBU], xq, m);
.LBB0_692:
	s_mul_hi_u32 s68, s11, 0xaaaaaaab
	s_mul_hi_u32 s71, s41, 0xaaaaaaab
	s_lshr_b32 s68, s68, 2
	s_lshr_b32 s71, s71, 2
	s_mul_i32 s72, s71, 6
	s_sub_u32 s72, s41, s72
	s_sub_u32 s72, s72, 5
	s_and_b32 s73, s71, 7
	s_sub_u32 s73, s73, s84
	s_or_b32 s85, s72, s73
	s_add_i32 s86, s71, 1
	s_lshl_b32 s86, s86, 21
	s_mulk_i32 s68, 0xc00
	s_mul_i32 s74, s71, 0xc00
	s_mulk_i32 s71, 0x1780
	s_add_i32 s69, s33, s10
	s_add_i32 s70, s33, s40
	v_subrev_u32_e32 v16, s68, v83
	v_subrev_u32_e32 v18, s74, v91
	v_subrev_u32_e32 v19, s71, v94
	v_subrev_u32_e32 v17, s74, v93
	v_add_u32_e32 v28, s69, v19
	v_add_u32_e32 v46, s70, v16
	v_add_u32_e32 v24, s70, v18
	v_add_u32_e32 v131, s70, v17
	ds_read_b128 v[16:19], v24 offset:16
	ds_read_b128 v[20:23], v24 offset:32
	ds_read_b128 v[24:27], v24 offset:48
	ds_read_b128 v[28:31], v28
	ds_read_b128 v[46:49], v46
	ds_read2_b32 v[70:71], v131 offset1:4
	s_mul_i32 s72, s11, 0x55800
	s_add_i32 s73, s72, 0x7faa800
	v_mov_b32_e32 v45, 0
	v_mov_b32_e32 v116, 0
	v_mov_b32_e32 v117, 0
	v_mov_b32_e32 v118, 0
	s_and_b32 s73, s73, 0x7e00000
	s_waitcnt lgkmcnt(5)
	v_mad_u32_u16 v16, v16, s48, v90
	v_mad_u32_u16 v50, v17, s48, v90
	v_mad_u32_u16 v51, v18, s48, v90
	v_mad_u32_u16 v52, v19, s48, v90
	s_waitcnt lgkmcnt(3)
	v_mad_u32_u16 v66, v24, s48, v90
	v_mad_u32_u16 v104, v25, s48, v90
	v_mad_u32_u16 v108, v26, s48, v90
	v_mad_u32_u16 v112, v27, s48, v90
	s_waitcnt vmcnt(3) lgkmcnt(2)
	v_dot4c_i32_i8_e32 v45, v12, v28
	s_waitcnt vmcnt(2)
	v_dot4c_i32_i8_e32 v116, v8, v28
	s_waitcnt vmcnt(1)
	v_dot4c_i32_i8_e32 v117, v4, v28
	s_waitcnt vmcnt(0)
	v_dot4c_i32_i8_e32 v118, v0, v28
	v_mad_u32_u16 v0, v20, s48, v90
	v_mad_u32_u16 v4, v21, s48, v90
	v_mad_u32_u16 v8, v22, s48, v90
	v_mad_u32_u16 v12, v23, s48, v90
	s_waitcnt lgkmcnt(1)
	v_mad_u32_u16 v132, v46, s48, v90
	v_mad_u32_u16 v133, v47, s48, v90
	v_mad_u32_u16 v134, v48, s48, v90
	v_mad_u32_u16 v135, v49, s48, v90
	buffer_load_dwordx4 v[16:19], v16, s[60:63], s73 offen
	s_nop 0
	buffer_load_dwordx4 v[20:23], v50, s[60:63], s73 offen
	buffer_load_dwordx4 v[24:27], v51, s[60:63], s73 offen
	buffer_load_dwordx4 v[46:49], v52, s[60:63], s73 offen
	s_nop 0
	buffer_load_dwordx4 v[50:53], v0, s[60:63], s73 offen
	buffer_load_dwordx4 v[54:57], v4, s[60:63], s73 offen
	buffer_load_dwordx4 v[58:61], v8, s[60:63], s73 offen
	buffer_load_dwordx4 v[62:65], v12, s[60:63], s73 offen
	s_nop 0
	buffer_load_dwordx4 v[66:69], v66, s[60:63], s73 offen
	s_nop 0
	buffer_load_dwordx4 v[104:107], v104, s[60:63], s73 offen
	s_nop 0
	buffer_load_dwordx4 v[108:111], v108, s[60:63], s73 offen
	s_nop 0
	buffer_load_dwordx4 v[112:115], v112, s[60:63], s73 offen
	v_dot4c_i32_i8_e32 v45, v13, v29
	v_dot4c_i32_i8_e32 v116, v9, v29
	v_dot4c_i32_i8_e32 v117, v5, v29
	v_dot4c_i32_i8_e32 v118, v1, v29
	s_and_b32 s72, s72, 0x7e00000
	v_dot4c_i32_i8_e32 v45, v14, v30
	v_dot4c_i32_i8_e32 v116, v10, v30
	v_dot4c_i32_i8_e32 v117, v6, v30
	v_dot4c_i32_i8_e32 v118, v2, v30
	v_dot4c_i32_i8_e32 v45, v15, v31
	v_dot4c_i32_i8_e32 v116, v11, v31
	v_dot4c_i32_i8_e32 v117, v7, v31
	v_dot4c_i32_i8_e32 v118, v3, v31
	buffer_load_dwordx4 v[12:15], v132, s[60:63], s72 offen
	buffer_load_dwordx4 v[8:11], v133, s[60:63], s72 offen
	buffer_load_dwordx4 v[4:7], v134, s[60:63], s72 offen
	buffer_load_dwordx4 v[0:3], v135, s[60:63], s72 offen
	s_cmp_lg_u32 s85, 0
	s_cbranch_scc1 .Lpf_skip
	buffer_load_dword v136, v137, s[60:63], s86 offen
	s_add_i32 s86, s86, 0x2000
	buffer_load_dword v136, v137, s[60:63], s86 offen
	s_add_i32 s86, s86, 0x2000
	buffer_load_dword v136, v137, s[60:63], s86 offen
	s_add_i32 s86, s86, 0x2000
	buffer_load_dword v136, v137, s[60:63], s86 offen
	s_add_i32 s86, s86, 0x2000
	buffer_load_dword v136, v137, s[60:63], s86 offen
	s_add_i32 s86, s86, 0x2000
	buffer_load_dword v136, v137, s[60:63], s86 offen
	s_add_i32 s86, s86, 0x2000
	buffer_load_dword v136, v137, s[60:63], s86 offen
	s_add_i32 s86, s86, 0x2000
	buffer_load_dword v136, v137, s[60:63], s86 offen
